# diff-lat inner block: cross-half row max (permlane32_swap) moved to the rare rescale path (any-lane test on the half-row max decides the same), row-sum accumulators start from an add
# speedup vs baseline: 1.3476x; 1.0115x over previous
.LBB0_727:
	v_add_u32_e32 v250, 0x2000, v163
	ds_read2_b64 v[142:145], v163 offset0:0 offset1:2
	ds_read2_b64 v[138:141], v163 offset0:4 offset1:6
	ds_read2_b64 v[134:137], v250 offset0:32 offset1:34
	ds_read2_b64 v[130:133], v250 offset0:36 offset1:38
	ds_read_b128 v[242:245], v161 offset:0
	ds_read_b128 v[246:249], v161 offset:32
	s_waitcnt lgkmcnt(0)
	v_mfma_f32_32x32x16_bf16 v[66:81], v[242:245], v[82:85], 0
	v_mfma_f32_32x32x16_bf16 v[66:81], v[246:249], v[86:89], v[66:81]
	s_nop 15
	v_max3_f32 v185, v66, v67, v68
	v_max3_f32 v185, v185, v69, v70
	v_max3_f32 v185, v185, v71, v72
	v_max3_f32 v185, v185, v73, v74
	v_max3_f32 v185, v185, v75, v76
	ds_read_b128 v[242:245], v161 offset:64
	ds_read_b128 v[246:249], v161 offset:96
	v_max3_f32 v185, v185, v77, v78
	v_max3_f32 v185, v185, v79, v80
	v_max_f32_e32 v185, v185, v81
	v_fma_f32 v188, v185, s75, -v224
	v_cmp_lt_f32_e32 vcc, s73, v188
	s_cbranch_vccz .Lda_dl_nr0
	v_mov_b32_e32 v188, v185
	s_nop 1
	v_permlane32_swap_b32_e32 v185, v188
	v_max_f32_e32 v185, v185, v188
	v_mul_f32_e32 v185, 0x3e8293ee, v185
	v_max_f32_e32 v185, v224, v185
	v_sub_f32_e32 v188, v224, v185
	v_exp_f32_e32 v188, v188
	v_mov_b32_e32 v224, v185
	s_nop 0
	v_mul_f32_e32 v157, v157, v188
	v_pk_mul_f32 v[50:51], v[50:51], v[188:189] op_sel_hi:[1,0]
	v_pk_mul_f32 v[52:53], v[52:53], v[188:189] op_sel_hi:[1,0]
	v_pk_mul_f32 v[54:55], v[54:55], v[188:189] op_sel_hi:[1,0]
	v_pk_mul_f32 v[56:57], v[56:57], v[188:189] op_sel_hi:[1,0]
	v_pk_mul_f32 v[58:59], v[58:59], v[188:189] op_sel_hi:[1,0]
	v_pk_mul_f32 v[60:61], v[60:61], v[188:189] op_sel_hi:[1,0]
	v_pk_mul_f32 v[62:63], v[62:63], v[188:189] op_sel_hi:[1,0]
	v_pk_mul_f32 v[64:65], v[64:65], v[188:189] op_sel_hi:[1,0]
	v_pk_mul_f32 v[18:19], v[18:19], v[188:189] op_sel_hi:[1,0]
	v_pk_mul_f32 v[20:21], v[20:21], v[188:189] op_sel_hi:[1,0]
	v_pk_mul_f32 v[22:23], v[22:23], v[188:189] op_sel_hi:[1,0]
	v_pk_mul_f32 v[24:25], v[24:25], v[188:189] op_sel_hi:[1,0]
	v_pk_mul_f32 v[26:27], v[26:27], v[188:189] op_sel_hi:[1,0]
	v_pk_mul_f32 v[28:29], v[28:29], v[188:189] op_sel_hi:[1,0]
	v_pk_mul_f32 v[30:31], v[30:31], v[188:189] op_sel_hi:[1,0]
	v_pk_mul_f32 v[32:33], v[32:33], v[188:189] op_sel_hi:[1,0]
.Lda_dl_nr0:
	v_fma_f32 v66, v66, s75, -v224
	v_exp_f32_e32 v66, v66
	v_fma_f32 v67, v67, s75, -v224
	v_exp_f32_e32 v67, v67
	v_fma_f32 v68, v68, s75, -v224
	v_exp_f32_e32 v68, v68
	v_fma_f32 v69, v69, s75, -v224
	v_exp_f32_e32 v69, v69
	v_add_f32_e32 v193, v68, v66
	v_fma_f32 v70, v70, s75, -v224
	s_waitcnt lgkmcnt(0)
	v_mfma_f32_32x32x16_bf16 v[226:241], v[242:245], v[90:93], 0
	v_exp_f32_e32 v70, v70
	v_add_f32_e32 v194, v69, v67
	v_fma_f32 v71, v71, s75, -v224
	v_exp_f32_e32 v71, v71
	v_add_f32_e32 v193, v70, v193
	v_fma_f32 v72, v72, s75, -v224
	v_exp_f32_e32 v72, v72
	v_add_f32_e32 v194, v71, v194
	v_fma_f32 v73, v73, s75, -v224
	v_exp_f32_e32 v73, v73
	v_add_f32_e32 v193, v72, v193
	v_fma_f32 v74, v74, s75, -v224
	v_exp_f32_e32 v74, v74
	v_add_f32_e32 v194, v73, v194
	v_fma_f32 v75, v75, s75, -v224
	v_exp_f32_e32 v75, v75
	v_add_f32_e32 v193, v74, v193
	v_fma_f32 v76, v76, s75, -v224
	v_mfma_f32_32x32x16_bf16 v[226:241], v[246:249], v[94:97], v[226:241]
	v_exp_f32_e32 v76, v76
	v_add_f32_e32 v194, v75, v194
	v_fma_f32 v77, v77, s75, -v224
	v_exp_f32_e32 v77, v77
	v_add_f32_e32 v193, v76, v193
	v_fma_f32 v78, v78, s75, -v224
	v_exp_f32_e32 v78, v78
	v_add_f32_e32 v194, v77, v194
	v_fma_f32 v79, v79, s75, -v224
	v_exp_f32_e32 v79, v79
	v_add_f32_e32 v193, v78, v193
	v_fma_f32 v80, v80, s75, -v224
	v_exp_f32_e32 v80, v80
	v_add_f32_e32 v194, v79, v194
	v_fma_f32 v81, v81, s75, -v224
	v_exp_f32_e32 v81, v81
	v_add_f32_e32 v193, v80, v193
	v_add_f32_e32 v194, v81, v194
	v_add_f32_e32 v193, v193, v194
	v_cvt_pk_bf16_f32 v242, v66, v67
	v_cvt_pk_bf16_f32 v243, v68, v69
	v_cvt_pk_bf16_f32 v244, v70, v71
	v_cvt_pk_bf16_f32 v245, v72, v73
	v_cvt_pk_bf16_f32 v246, v74, v75
	v_cvt_pk_bf16_f32 v247, v76, v77
	v_cvt_pk_bf16_f32 v248, v78, v79
	v_cvt_pk_bf16_f32 v249, v80, v81
	v_add_f32_e32 v157, v157, v193
	s_waitcnt lgkmcnt(0)
	s_nop 1
	v_mfma_f32_32x32x16_bf16 v[50:65], v[142:145], v[242:245], v[50:65]
	v_max3_f32 v185, v226, v227, v228
	v_mfma_f32_32x32x16_bf16 v[18:33], v[134:137], v[242:245], v[18:33]
	ds_read_b128 v[242:245], v161 offset:4608
	v_max3_f32 v185, v185, v229, v230
	v_max3_f32 v185, v185, v231, v232
	v_mfma_f32_32x32x16_bf16 v[50:65], v[138:141], v[246:249], v[50:65]
	v_max3_f32 v185, v185, v233, v234
	v_max3_f32 v185, v185, v235, v236
	v_mfma_f32_32x32x16_bf16 v[18:33], v[130:133], v[246:249], v[18:33]
	ds_read_b128 v[246:249], v161 offset:4640
	v_max3_f32 v185, v185, v237, v238
	v_max3_f32 v185, v185, v239, v240
	v_max_f32_e32 v185, v185, v241
	v_fma_f32 v188, v185, s75, -v223
	v_cmp_lt_f32_e32 vcc, s73, v188
	s_cbranch_vccz .Lda_dl_nr1
	v_mov_b32_e32 v188, v185
	s_nop 1
	v_permlane32_swap_b32_e32 v185, v188
	v_max_f32_e32 v185, v185, v188
	v_mul_f32_e32 v185, 0x3e8293ee, v185
	v_max_f32_e32 v185, v223, v185
	v_sub_f32_e32 v188, v223, v185
	v_exp_f32_e32 v188, v188
	v_mov_b32_e32 v223, v185
	s_nop 0
	v_mul_f32_e32 v155, v155, v188
	v_pk_mul_f32 v[34:35], v[34:35], v[188:189] op_sel_hi:[1,0]
	v_pk_mul_f32 v[36:37], v[36:37], v[188:189] op_sel_hi:[1,0]
	v_pk_mul_f32 v[38:39], v[38:39], v[188:189] op_sel_hi:[1,0]
	v_pk_mul_f32 v[40:41], v[40:41], v[188:189] op_sel_hi:[1,0]
	v_pk_mul_f32 v[42:43], v[42:43], v[188:189] op_sel_hi:[1,0]
	v_pk_mul_f32 v[44:45], v[44:45], v[188:189] op_sel_hi:[1,0]
	v_pk_mul_f32 v[46:47], v[46:47], v[188:189] op_sel_hi:[1,0]
	v_pk_mul_f32 v[48:49], v[48:49], v[188:189] op_sel_hi:[1,0]
	v_pk_mul_f32 v[2:3], v[2:3], v[188:189] op_sel_hi:[1,0]
	v_pk_mul_f32 v[4:5], v[4:5], v[188:189] op_sel_hi:[1,0]
	v_pk_mul_f32 v[6:7], v[6:7], v[188:189] op_sel_hi:[1,0]
	v_pk_mul_f32 v[8:9], v[8:9], v[188:189] op_sel_hi:[1,0]
	v_pk_mul_f32 v[10:11], v[10:11], v[188:189] op_sel_hi:[1,0]
	v_pk_mul_f32 v[12:13], v[12:13], v[188:189] op_sel_hi:[1,0]
	v_pk_mul_f32 v[14:15], v[14:15], v[188:189] op_sel_hi:[1,0]
	v_pk_mul_f32 v[16:17], v[16:17], v[188:189] op_sel_hi:[1,0]
.Lda_dl_nr1:
	v_fma_f32 v226, v226, s75, -v223
	v_exp_f32_e32 v226, v226
	v_fma_f32 v227, v227, s75, -v223
	v_exp_f32_e32 v227, v227
	v_fma_f32 v228, v228, s75, -v223
	v_exp_f32_e32 v228, v228
	v_fma_f32 v229, v229, s75, -v223
	v_exp_f32_e32 v229, v229
	v_add_f32_e32 v193, v228, v226
	v_fma_f32 v230, v230, s75, -v223
	s_waitcnt lgkmcnt(0)
	v_mfma_f32_32x32x16_bf16 v[66:81], v[242:245], v[82:85], 0
	v_exp_f32_e32 v230, v230
	v_add_f32_e32 v194, v229, v227
	v_fma_f32 v231, v231, s75, -v223
	v_exp_f32_e32 v231, v231
	v_add_f32_e32 v193, v230, v193
	v_fma_f32 v232, v232, s75, -v223
	v_exp_f32_e32 v232, v232
	v_add_f32_e32 v194, v231, v194
	v_fma_f32 v233, v233, s75, -v223
	v_exp_f32_e32 v233, v233
	v_add_f32_e32 v193, v232, v193
	v_fma_f32 v234, v234, s75, -v223
	v_exp_f32_e32 v234, v234
	v_add_f32_e32 v194, v233, v194
	v_fma_f32 v235, v235, s75, -v223
	v_exp_f32_e32 v235, v235
	v_add_f32_e32 v193, v234, v193
	v_fma_f32 v236, v236, s75, -v223
	v_mfma_f32_32x32x16_bf16 v[66:81], v[246:249], v[86:89], v[66:81]
	v_exp_f32_e32 v236, v236
	v_add_f32_e32 v194, v235, v194
	v_fma_f32 v237, v237, s75, -v223
	v_exp_f32_e32 v237, v237
	v_add_f32_e32 v193, v236, v193
	v_fma_f32 v238, v238, s75, -v223
	v_exp_f32_e32 v238, v238
	v_add_f32_e32 v194, v237, v194
	v_fma_f32 v239, v239, s75, -v223
	v_exp_f32_e32 v239, v239
	v_add_f32_e32 v193, v238, v193
	v_fma_f32 v240, v240, s75, -v223
	v_exp_f32_e32 v240, v240
	v_add_f32_e32 v194, v239, v194
	v_fma_f32 v241, v241, s75, -v223
	v_exp_f32_e32 v241, v241
	v_add_f32_e32 v193, v240, v193
	v_add_f32_e32 v194, v241, v194
	v_add_f32_e32 v193, v193, v194
	v_cvt_pk_bf16_f32 v242, v226, v227
	v_cvt_pk_bf16_f32 v243, v228, v229
	v_cvt_pk_bf16_f32 v244, v230, v231
	v_cvt_pk_bf16_f32 v245, v232, v233
	v_cvt_pk_bf16_f32 v246, v234, v235
	v_cvt_pk_bf16_f32 v247, v236, v237
	v_cvt_pk_bf16_f32 v248, v238, v239
	v_cvt_pk_bf16_f32 v249, v240, v241
	v_add_f32_e32 v155, v155, v193
	s_nop 1
	v_mfma_f32_32x32x16_bf16 v[34:49], v[142:145], v[242:245], v[34:49]
	v_max3_f32 v185, v66, v67, v68
	v_mfma_f32_32x32x16_bf16 v[2:17], v[134:137], v[242:245], v[2:17]
	ds_read_b128 v[242:245], v161 offset:4672
	v_max3_f32 v185, v185, v69, v70
	v_max3_f32 v185, v185, v71, v72
	v_mfma_f32_32x32x16_bf16 v[34:49], v[138:141], v[246:249], v[34:49]
	v_max3_f32 v185, v185, v73, v74
	v_max3_f32 v185, v185, v75, v76
	v_mfma_f32_32x32x16_bf16 v[2:17], v[130:133], v[246:249], v[2:17]
	ds_read_b128 v[246:249], v161 offset:4704
	ds_read2_b64 v[142:145], v163 offset0:8 offset1:10
	ds_read2_b64 v[138:141], v163 offset0:12 offset1:14
	ds_read2_b64 v[134:137], v250 offset0:40 offset1:42
	ds_read2_b64 v[130:133], v250 offset0:44 offset1:46
	v_max3_f32 v185, v185, v77, v78
	v_max3_f32 v185, v185, v79, v80
	v_max_f32_e32 v185, v185, v81
	v_fma_f32 v188, v185, s75, -v224
	v_cmp_lt_f32_e32 vcc, s73, v188
	s_cbranch_vccz .Lda_dl_nr2
	v_mov_b32_e32 v188, v185
	s_nop 1
	v_permlane32_swap_b32_e32 v185, v188
	v_max_f32_e32 v185, v185, v188
	v_mul_f32_e32 v185, 0x3e8293ee, v185
	v_max_f32_e32 v185, v224, v185
	v_sub_f32_e32 v188, v224, v185
	v_exp_f32_e32 v188, v188
	v_mov_b32_e32 v224, v185
	s_nop 0
	v_mul_f32_e32 v157, v157, v188
	v_pk_mul_f32 v[50:51], v[50:51], v[188:189] op_sel_hi:[1,0]
	v_pk_mul_f32 v[52:53], v[52:53], v[188:189] op_sel_hi:[1,0]
	v_pk_mul_f32 v[54:55], v[54:55], v[188:189] op_sel_hi:[1,0]
	v_pk_mul_f32 v[56:57], v[56:57], v[188:189] op_sel_hi:[1,0]
	v_pk_mul_f32 v[58:59], v[58:59], v[188:189] op_sel_hi:[1,0]
	v_pk_mul_f32 v[60:61], v[60:61], v[188:189] op_sel_hi:[1,0]
	v_pk_mul_f32 v[62:63], v[62:63], v[188:189] op_sel_hi:[1,0]
	v_pk_mul_f32 v[64:65], v[64:65], v[188:189] op_sel_hi:[1,0]
	v_pk_mul_f32 v[18:19], v[18:19], v[188:189] op_sel_hi:[1,0]
	v_pk_mul_f32 v[20:21], v[20:21], v[188:189] op_sel_hi:[1,0]
	v_pk_mul_f32 v[22:23], v[22:23], v[188:189] op_sel_hi:[1,0]
	v_pk_mul_f32 v[24:25], v[24:25], v[188:189] op_sel_hi:[1,0]
	v_pk_mul_f32 v[26:27], v[26:27], v[188:189] op_sel_hi:[1,0]
	v_pk_mul_f32 v[28:29], v[28:29], v[188:189] op_sel_hi:[1,0]
	v_pk_mul_f32 v[30:31], v[30:31], v[188:189] op_sel_hi:[1,0]
	v_pk_mul_f32 v[32:33], v[32:33], v[188:189] op_sel_hi:[1,0]
.Lda_dl_nr2:
	v_fma_f32 v66, v66, s75, -v224
	v_exp_f32_e32 v66, v66
	v_fma_f32 v67, v67, s75, -v224
	v_exp_f32_e32 v67, v67
	v_fma_f32 v68, v68, s75, -v224
	v_exp_f32_e32 v68, v68
	v_fma_f32 v69, v69, s75, -v224
	v_exp_f32_e32 v69, v69
	v_add_f32_e32 v193, v68, v66
	v_fma_f32 v70, v70, s75, -v224
	s_waitcnt lgkmcnt(4)
	v_mfma_f32_32x32x16_bf16 v[226:241], v[242:245], v[90:93], 0
	v_exp_f32_e32 v70, v70
	v_add_f32_e32 v194, v69, v67
	v_fma_f32 v71, v71, s75, -v224
	v_exp_f32_e32 v71, v71
	v_add_f32_e32 v193, v70, v193
	v_fma_f32 v72, v72, s75, -v224
	v_exp_f32_e32 v72, v72
	v_add_f32_e32 v194, v71, v194
	v_fma_f32 v73, v73, s75, -v224
	v_exp_f32_e32 v73, v73
	v_add_f32_e32 v193, v72, v193
	v_fma_f32 v74, v74, s75, -v224
	v_exp_f32_e32 v74, v74
	v_add_f32_e32 v194, v73, v194
	v_fma_f32 v75, v75, s75, -v224
	v_exp_f32_e32 v75, v75
	v_add_f32_e32 v193, v74, v193
	v_fma_f32 v76, v76, s75, -v224
	v_mfma_f32_32x32x16_bf16 v[226:241], v[246:249], v[94:97], v[226:241]
	v_exp_f32_e32 v76, v76
	v_add_f32_e32 v194, v75, v194
	v_fma_f32 v77, v77, s75, -v224
	v_exp_f32_e32 v77, v77
	v_add_f32_e32 v193, v76, v193
	v_fma_f32 v78, v78, s75, -v224
	v_exp_f32_e32 v78, v78
	v_add_f32_e32 v194, v77, v194
	v_fma_f32 v79, v79, s75, -v224
	v_exp_f32_e32 v79, v79
	v_add_f32_e32 v193, v78, v193
	v_fma_f32 v80, v80, s75, -v224
	v_exp_f32_e32 v80, v80
	v_add_f32_e32 v194, v79, v194
	v_fma_f32 v81, v81, s75, -v224
	v_exp_f32_e32 v81, v81
	v_add_f32_e32 v193, v80, v193
	v_add_f32_e32 v194, v81, v194
	v_add_f32_e32 v193, v193, v194
	v_cvt_pk_bf16_f32 v242, v66, v67
	v_cvt_pk_bf16_f32 v243, v68, v69
	v_cvt_pk_bf16_f32 v244, v70, v71
	v_cvt_pk_bf16_f32 v245, v72, v73
	v_cvt_pk_bf16_f32 v246, v74, v75
	v_cvt_pk_bf16_f32 v247, v76, v77
	v_cvt_pk_bf16_f32 v248, v78, v79
	v_cvt_pk_bf16_f32 v249, v80, v81
	v_add_f32_e32 v157, v157, v193
	s_waitcnt lgkmcnt(0)
	s_nop 1
	v_mfma_f32_32x32x16_bf16 v[50:65], v[142:145], v[242:245], v[50:65]
	v_max3_f32 v185, v226, v227, v228
	v_mfma_f32_32x32x16_bf16 v[18:33], v[134:137], v[242:245], v[18:33]
	ds_read_b128 v[242:245], v161 offset:9216
	v_max3_f32 v185, v185, v229, v230
	v_max3_f32 v185, v185, v231, v232
	v_mfma_f32_32x32x16_bf16 v[50:65], v[138:141], v[246:249], v[50:65]
	v_max3_f32 v185, v185, v233, v234
	v_max3_f32 v185, v185, v235, v236
	v_mfma_f32_32x32x16_bf16 v[18:33], v[130:133], v[246:249], v[18:33]
	ds_read_b128 v[246:249], v161 offset:9248
	v_max3_f32 v185, v185, v237, v238
	v_max3_f32 v185, v185, v239, v240
	v_max_f32_e32 v185, v185, v241
	v_fma_f32 v188, v185, s75, -v223
	v_cmp_lt_f32_e32 vcc, s73, v188
	s_cbranch_vccz .Lda_dl_nr3
	v_mov_b32_e32 v188, v185
	s_nop 1
	v_permlane32_swap_b32_e32 v185, v188
	v_max_f32_e32 v185, v185, v188
	v_mul_f32_e32 v185, 0x3e8293ee, v185
	v_max_f32_e32 v185, v223, v185
	v_sub_f32_e32 v188, v223, v185
	v_exp_f32_e32 v188, v188
	v_mov_b32_e32 v223, v185
	s_nop 0
	v_mul_f32_e32 v155, v155, v188
	v_pk_mul_f32 v[34:35], v[34:35], v[188:189] op_sel_hi:[1,0]
	v_pk_mul_f32 v[36:37], v[36:37], v[188:189] op_sel_hi:[1,0]
	v_pk_mul_f32 v[38:39], v[38:39], v[188:189] op_sel_hi:[1,0]
	v_pk_mul_f32 v[40:41], v[40:41], v[188:189] op_sel_hi:[1,0]
	v_pk_mul_f32 v[42:43], v[42:43], v[188:189] op_sel_hi:[1,0]
	v_pk_mul_f32 v[44:45], v[44:45], v[188:189] op_sel_hi:[1,0]
	v_pk_mul_f32 v[46:47], v[46:47], v[188:189] op_sel_hi:[1,0]
	v_pk_mul_f32 v[48:49], v[48:49], v[188:189] op_sel_hi:[1,0]
	v_pk_mul_f32 v[2:3], v[2:3], v[188:189] op_sel_hi:[1,0]
	v_pk_mul_f32 v[4:5], v[4:5], v[188:189] op_sel_hi:[1,0]
	v_pk_mul_f32 v[6:7], v[6:7], v[188:189] op_sel_hi:[1,0]
	v_pk_mul_f32 v[8:9], v[8:9], v[188:189] op_sel_hi:[1,0]
	v_pk_mul_f32 v[10:11], v[10:11], v[188:189] op_sel_hi:[1,0]
	v_pk_mul_f32 v[12:13], v[12:13], v[188:189] op_sel_hi:[1,0]
	v_pk_mul_f32 v[14:15], v[14:15], v[188:189] op_sel_hi:[1,0]
	v_pk_mul_f32 v[16:17], v[16:17], v[188:189] op_sel_hi:[1,0]
.Lda_dl_nr3:
	v_fma_f32 v226, v226, s75, -v223
	v_exp_f32_e32 v226, v226
	v_fma_f32 v227, v227, s75, -v223
	v_exp_f32_e32 v227, v227
	v_fma_f32 v228, v228, s75, -v223
	v_exp_f32_e32 v228, v228
	v_fma_f32 v229, v229, s75, -v223
	v_exp_f32_e32 v229, v229
	v_add_f32_e32 v193, v228, v226
	v_fma_f32 v230, v230, s75, -v223
	s_waitcnt lgkmcnt(0)
	v_mfma_f32_32x32x16_bf16 v[66:81], v[242:245], v[82:85], 0
	v_exp_f32_e32 v230, v230
	v_add_f32_e32 v194, v229, v227
	v_fma_f32 v231, v231, s75, -v223
	v_exp_f32_e32 v231, v231
	v_add_f32_e32 v193, v230, v193
	v_fma_f32 v232, v232, s75, -v223
	v_exp_f32_e32 v232, v232
	v_add_f32_e32 v194, v231, v194
	v_fma_f32 v233, v233, s75, -v223
	v_exp_f32_e32 v233, v233
	v_add_f32_e32 v193, v232, v193
	v_fma_f32 v234, v234, s75, -v223
	v_exp_f32_e32 v234, v234
	v_add_f32_e32 v194, v233, v194
	v_fma_f32 v235, v235, s75, -v223
	v_exp_f32_e32 v235, v235
	v_add_f32_e32 v193, v234, v193
	v_fma_f32 v236, v236, s75, -v223
	v_mfma_f32_32x32x16_bf16 v[66:81], v[246:249], v[86:89], v[66:81]
	v_exp_f32_e32 v236, v236
	v_add_f32_e32 v194, v235, v194
	v_fma_f32 v237, v237, s75, -v223
	v_exp_f32_e32 v237, v237
	v_add_f32_e32 v193, v236, v193
	v_fma_f32 v238, v238, s75, -v223
	v_exp_f32_e32 v238, v238
	v_add_f32_e32 v194, v237, v194
	v_fma_f32 v239, v239, s75, -v223
	v_exp_f32_e32 v239, v239
	v_add_f32_e32 v193, v238, v193
	v_fma_f32 v240, v240, s75, -v223
	v_exp_f32_e32 v240, v240
	v_add_f32_e32 v194, v239, v194
	v_fma_f32 v241, v241, s75, -v223
	v_exp_f32_e32 v241, v241
	v_add_f32_e32 v193, v240, v193
	v_add_f32_e32 v194, v241, v194
	v_add_f32_e32 v193, v193, v194
	v_cvt_pk_bf16_f32 v242, v226, v227
	v_cvt_pk_bf16_f32 v243, v228, v229
	v_cvt_pk_bf16_f32 v244, v230, v231
	v_cvt_pk_bf16_f32 v245, v232, v233
	v_cvt_pk_bf16_f32 v246, v234, v235
	v_cvt_pk_bf16_f32 v247, v236, v237
	v_cvt_pk_bf16_f32 v248, v238, v239
	v_cvt_pk_bf16_f32 v249, v240, v241
	v_add_f32_e32 v155, v155, v193
	s_nop 1
	v_mfma_f32_32x32x16_bf16 v[34:49], v[142:145], v[242:245], v[34:49]
	v_max3_f32 v185, v66, v67, v68
	v_mfma_f32_32x32x16_bf16 v[2:17], v[134:137], v[242:245], v[2:17]
	ds_read_b128 v[242:245], v161 offset:9280
	v_max3_f32 v185, v185, v69, v70
	v_max3_f32 v185, v185, v71, v72
	v_mfma_f32_32x32x16_bf16 v[34:49], v[138:141], v[246:249], v[34:49]
	v_max3_f32 v185, v185, v73, v74
	v_max3_f32 v185, v185, v75, v76
	v_mfma_f32_32x32x16_bf16 v[2:17], v[130:133], v[246:249], v[2:17]
	ds_read_b128 v[246:249], v161 offset:9312
	ds_read2_b64 v[142:145], v163 offset0:16 offset1:18
	ds_read2_b64 v[138:141], v163 offset0:20 offset1:22
	ds_read2_b64 v[134:137], v250 offset0:48 offset1:50
	ds_read2_b64 v[130:133], v250 offset0:52 offset1:54
	v_max3_f32 v185, v185, v77, v78
	v_max3_f32 v185, v185, v79, v80
	v_max_f32_e32 v185, v185, v81
	v_fma_f32 v188, v185, s75, -v224
	v_cmp_lt_f32_e32 vcc, s73, v188
	s_cbranch_vccz .Lda_dl_nr4
	v_mov_b32_e32 v188, v185
	s_nop 1
	v_permlane32_swap_b32_e32 v185, v188
	v_max_f32_e32 v185, v185, v188
	v_mul_f32_e32 v185, 0x3e8293ee, v185
	v_max_f32_e32 v185, v224, v185
	v_sub_f32_e32 v188, v224, v185
	v_exp_f32_e32 v188, v188
	v_mov_b32_e32 v224, v185
	s_nop 0
	v_mul_f32_e32 v157, v157, v188
	v_pk_mul_f32 v[50:51], v[50:51], v[188:189] op_sel_hi:[1,0]
	v_pk_mul_f32 v[52:53], v[52:53], v[188:189] op_sel_hi:[1,0]
	v_pk_mul_f32 v[54:55], v[54:55], v[188:189] op_sel_hi:[1,0]
	v_pk_mul_f32 v[56:57], v[56:57], v[188:189] op_sel_hi:[1,0]
	v_pk_mul_f32 v[58:59], v[58:59], v[188:189] op_sel_hi:[1,0]
	v_pk_mul_f32 v[60:61], v[60:61], v[188:189] op_sel_hi:[1,0]
	v_pk_mul_f32 v[62:63], v[62:63], v[188:189] op_sel_hi:[1,0]
	v_pk_mul_f32 v[64:65], v[64:65], v[188:189] op_sel_hi:[1,0]
	v_pk_mul_f32 v[18:19], v[18:19], v[188:189] op_sel_hi:[1,0]
	v_pk_mul_f32 v[20:21], v[20:21], v[188:189] op_sel_hi:[1,0]
	v_pk_mul_f32 v[22:23], v[22:23], v[188:189] op_sel_hi:[1,0]
	v_pk_mul_f32 v[24:25], v[24:25], v[188:189] op_sel_hi:[1,0]
	v_pk_mul_f32 v[26:27], v[26:27], v[188:189] op_sel_hi:[1,0]
	v_pk_mul_f32 v[28:29], v[28:29], v[188:189] op_sel_hi:[1,0]
	v_pk_mul_f32 v[30:31], v[30:31], v[188:189] op_sel_hi:[1,0]
	v_pk_mul_f32 v[32:33], v[32:33], v[188:189] op_sel_hi:[1,0]
.Lda_dl_nr4:
	v_fma_f32 v66, v66, s75, -v224
	v_exp_f32_e32 v66, v66
	v_fma_f32 v67, v67, s75, -v224
	v_exp_f32_e32 v67, v67
	v_fma_f32 v68, v68, s75, -v224
	v_exp_f32_e32 v68, v68
	v_fma_f32 v69, v69, s75, -v224
	v_exp_f32_e32 v69, v69
	v_add_f32_e32 v193, v68, v66
	v_fma_f32 v70, v70, s75, -v224
	s_waitcnt lgkmcnt(4)
	v_mfma_f32_32x32x16_bf16 v[226:241], v[242:245], v[90:93], 0
	v_exp_f32_e32 v70, v70
	v_add_f32_e32 v194, v69, v67
	v_fma_f32 v71, v71, s75, -v224
	v_exp_f32_e32 v71, v71
	v_add_f32_e32 v193, v70, v193
	v_fma_f32 v72, v72, s75, -v224
	v_exp_f32_e32 v72, v72
	v_add_f32_e32 v194, v71, v194
	v_fma_f32 v73, v73, s75, -v224
	v_exp_f32_e32 v73, v73
	v_add_f32_e32 v193, v72, v193
	v_fma_f32 v74, v74, s75, -v224
	v_exp_f32_e32 v74, v74
	v_add_f32_e32 v194, v73, v194
	v_fma_f32 v75, v75, s75, -v224
	v_exp_f32_e32 v75, v75
	v_add_f32_e32 v193, v74, v193
	v_fma_f32 v76, v76, s75, -v224
	v_mfma_f32_32x32x16_bf16 v[226:241], v[246:249], v[94:97], v[226:241]
	v_exp_f32_e32 v76, v76
	v_add_f32_e32 v194, v75, v194
	v_fma_f32 v77, v77, s75, -v224
	v_exp_f32_e32 v77, v77
	v_add_f32_e32 v193, v76, v193
	v_fma_f32 v78, v78, s75, -v224
	v_exp_f32_e32 v78, v78
	v_add_f32_e32 v194, v77, v194
	v_fma_f32 v79, v79, s75, -v224
	v_exp_f32_e32 v79, v79
	v_add_f32_e32 v193, v78, v193
	v_fma_f32 v80, v80, s75, -v224
	v_exp_f32_e32 v80, v80
	v_add_f32_e32 v194, v79, v194
	v_fma_f32 v81, v81, s75, -v224
	v_exp_f32_e32 v81, v81
	v_add_f32_e32 v193, v80, v193
	v_add_f32_e32 v194, v81, v194
	v_add_f32_e32 v193, v193, v194
	v_cvt_pk_bf16_f32 v242, v66, v67
	v_cvt_pk_bf16_f32 v243, v68, v69
	v_cvt_pk_bf16_f32 v244, v70, v71
	v_cvt_pk_bf16_f32 v245, v72, v73
	v_cvt_pk_bf16_f32 v246, v74, v75
	v_cvt_pk_bf16_f32 v247, v76, v77
	v_cvt_pk_bf16_f32 v248, v78, v79
	v_cvt_pk_bf16_f32 v249, v80, v81
	v_add_f32_e32 v157, v157, v193
	s_waitcnt lgkmcnt(0)
	s_nop 1
	v_mfma_f32_32x32x16_bf16 v[50:65], v[142:145], v[242:245], v[50:65]
	v_max3_f32 v185, v226, v227, v228
	v_mfma_f32_32x32x16_bf16 v[18:33], v[134:137], v[242:245], v[18:33]
	ds_read_b128 v[242:245], v161 offset:13824
	v_max3_f32 v185, v185, v229, v230
	v_max3_f32 v185, v185, v231, v232
	v_mfma_f32_32x32x16_bf16 v[50:65], v[138:141], v[246:249], v[50:65]
	v_max3_f32 v185, v185, v233, v234
	v_max3_f32 v185, v185, v235, v236
	v_mfma_f32_32x32x16_bf16 v[18:33], v[130:133], v[246:249], v[18:33]
	ds_read_b128 v[246:249], v161 offset:13856
	v_max3_f32 v185, v185, v237, v238
	v_max3_f32 v185, v185, v239, v240
	v_max_f32_e32 v185, v185, v241
	v_fma_f32 v188, v185, s75, -v223
	v_cmp_lt_f32_e32 vcc, s73, v188
	s_cbranch_vccz .Lda_dl_nr5
	v_mov_b32_e32 v188, v185
	s_nop 1
	v_permlane32_swap_b32_e32 v185, v188
	v_max_f32_e32 v185, v185, v188
	v_mul_f32_e32 v185, 0x3e8293ee, v185
	v_max_f32_e32 v185, v223, v185
	v_sub_f32_e32 v188, v223, v185
	v_exp_f32_e32 v188, v188
	v_mov_b32_e32 v223, v185
	s_nop 0
	v_mul_f32_e32 v155, v155, v188
	v_pk_mul_f32 v[34:35], v[34:35], v[188:189] op_sel_hi:[1,0]
	v_pk_mul_f32 v[36:37], v[36:37], v[188:189] op_sel_hi:[1,0]
	v_pk_mul_f32 v[38:39], v[38:39], v[188:189] op_sel_hi:[1,0]
	v_pk_mul_f32 v[40:41], v[40:41], v[188:189] op_sel_hi:[1,0]
	v_pk_mul_f32 v[42:43], v[42:43], v[188:189] op_sel_hi:[1,0]
	v_pk_mul_f32 v[44:45], v[44:45], v[188:189] op_sel_hi:[1,0]
	v_pk_mul_f32 v[46:47], v[46:47], v[188:189] op_sel_hi:[1,0]
	v_pk_mul_f32 v[48:49], v[48:49], v[188:189] op_sel_hi:[1,0]
	v_pk_mul_f32 v[2:3], v[2:3], v[188:189] op_sel_hi:[1,0]
	v_pk_mul_f32 v[4:5], v[4:5], v[188:189] op_sel_hi:[1,0]
	v_pk_mul_f32 v[6:7], v[6:7], v[188:189] op_sel_hi:[1,0]
	v_pk_mul_f32 v[8:9], v[8:9], v[188:189] op_sel_hi:[1,0]
	v_pk_mul_f32 v[10:11], v[10:11], v[188:189] op_sel_hi:[1,0]
	v_pk_mul_f32 v[12:13], v[12:13], v[188:189] op_sel_hi:[1,0]
	v_pk_mul_f32 v[14:15], v[14:15], v[188:189] op_sel_hi:[1,0]
	v_pk_mul_f32 v[16:17], v[16:17], v[188:189] op_sel_hi:[1,0]
.Lda_dl_nr5:
	v_fma_f32 v226, v226, s75, -v223
	v_exp_f32_e32 v226, v226
	v_fma_f32 v227, v227, s75, -v223
	v_exp_f32_e32 v227, v227
	v_fma_f32 v228, v228, s75, -v223
	v_exp_f32_e32 v228, v228
	v_fma_f32 v229, v229, s75, -v223
	v_exp_f32_e32 v229, v229
	v_add_f32_e32 v193, v228, v226
	v_fma_f32 v230, v230, s75, -v223
	s_waitcnt lgkmcnt(0)
	v_mfma_f32_32x32x16_bf16 v[66:81], v[242:245], v[82:85], 0
	v_exp_f32_e32 v230, v230
	v_add_f32_e32 v194, v229, v227
	v_fma_f32 v231, v231, s75, -v223
	v_exp_f32_e32 v231, v231
	v_add_f32_e32 v193, v230, v193
	v_fma_f32 v232, v232, s75, -v223
	v_exp_f32_e32 v232, v232
	v_add_f32_e32 v194, v231, v194
	v_fma_f32 v233, v233, s75, -v223
	v_exp_f32_e32 v233, v233
	v_add_f32_e32 v193, v232, v193
	v_fma_f32 v234, v234, s75, -v223
	v_exp_f32_e32 v234, v234
	v_add_f32_e32 v194, v233, v194
	v_fma_f32 v235, v235, s75, -v223
	v_exp_f32_e32 v235, v235
	v_add_f32_e32 v193, v234, v193
	v_fma_f32 v236, v236, s75, -v223
	v_mfma_f32_32x32x16_bf16 v[66:81], v[246:249], v[86:89], v[66:81]
	v_exp_f32_e32 v236, v236
	v_add_f32_e32 v194, v235, v194
	v_fma_f32 v237, v237, s75, -v223
	v_exp_f32_e32 v237, v237
	v_add_f32_e32 v193, v236, v193
	v_fma_f32 v238, v238, s75, -v223
	v_exp_f32_e32 v238, v238
	v_add_f32_e32 v194, v237, v194
	v_fma_f32 v239, v239, s75, -v223
	v_exp_f32_e32 v239, v239
	v_add_f32_e32 v193, v238, v193
	v_fma_f32 v240, v240, s75, -v223
	v_exp_f32_e32 v240, v240
	v_add_f32_e32 v194, v239, v194
	v_fma_f32 v241, v241, s75, -v223
	v_exp_f32_e32 v241, v241
	v_add_f32_e32 v193, v240, v193
	v_add_f32_e32 v194, v241, v194
	v_add_f32_e32 v193, v193, v194
	v_cvt_pk_bf16_f32 v242, v226, v227
	v_cvt_pk_bf16_f32 v243, v228, v229
	v_cvt_pk_bf16_f32 v244, v230, v231
	v_cvt_pk_bf16_f32 v245, v232, v233
	v_cvt_pk_bf16_f32 v246, v234, v235
	v_cvt_pk_bf16_f32 v247, v236, v237
	v_cvt_pk_bf16_f32 v248, v238, v239
	v_cvt_pk_bf16_f32 v249, v240, v241
	v_add_f32_e32 v155, v155, v193
	s_nop 1
	v_mfma_f32_32x32x16_bf16 v[34:49], v[142:145], v[242:245], v[34:49]
	v_max3_f32 v185, v66, v67, v68
	v_mfma_f32_32x32x16_bf16 v[2:17], v[134:137], v[242:245], v[2:17]
	ds_read_b128 v[242:245], v161 offset:13888
	v_max3_f32 v185, v185, v69, v70
	v_max3_f32 v185, v185, v71, v72
	v_mfma_f32_32x32x16_bf16 v[34:49], v[138:141], v[246:249], v[34:49]
	v_max3_f32 v185, v185, v73, v74
	v_max3_f32 v185, v185, v75, v76
	v_mfma_f32_32x32x16_bf16 v[2:17], v[130:133], v[246:249], v[2:17]
	ds_read_b128 v[246:249], v161 offset:13920
	ds_read2_b64 v[142:145], v163 offset0:24 offset1:26
	ds_read2_b64 v[138:141], v163 offset0:28 offset1:30
	ds_read2_b64 v[134:137], v250 offset0:56 offset1:58
	ds_read2_b64 v[130:133], v250 offset0:60 offset1:62
	v_max3_f32 v185, v185, v77, v78
	v_max3_f32 v185, v185, v79, v80
	v_max_f32_e32 v185, v185, v81
	v_fma_f32 v188, v185, s75, -v224
	v_cmp_lt_f32_e32 vcc, s73, v188
	s_cbranch_vccz .Lda_dl_nr6
	v_mov_b32_e32 v188, v185
	s_nop 1
	v_permlane32_swap_b32_e32 v185, v188
	v_max_f32_e32 v185, v185, v188
	v_mul_f32_e32 v185, 0x3e8293ee, v185
	v_max_f32_e32 v185, v224, v185
	v_sub_f32_e32 v188, v224, v185
	v_exp_f32_e32 v188, v188
	v_mov_b32_e32 v224, v185
	s_nop 0
	v_mul_f32_e32 v157, v157, v188
	v_pk_mul_f32 v[50:51], v[50:51], v[188:189] op_sel_hi:[1,0]
	v_pk_mul_f32 v[52:53], v[52:53], v[188:189] op_sel_hi:[1,0]
	v_pk_mul_f32 v[54:55], v[54:55], v[188:189] op_sel_hi:[1,0]
	v_pk_mul_f32 v[56:57], v[56:57], v[188:189] op_sel_hi:[1,0]
	v_pk_mul_f32 v[58:59], v[58:59], v[188:189] op_sel_hi:[1,0]
	v_pk_mul_f32 v[60:61], v[60:61], v[188:189] op_sel_hi:[1,0]
	v_pk_mul_f32 v[62:63], v[62:63], v[188:189] op_sel_hi:[1,0]
	v_pk_mul_f32 v[64:65], v[64:65], v[188:189] op_sel_hi:[1,0]
	v_pk_mul_f32 v[18:19], v[18:19], v[188:189] op_sel_hi:[1,0]
	v_pk_mul_f32 v[20:21], v[20:21], v[188:189] op_sel_hi:[1,0]
	v_pk_mul_f32 v[22:23], v[22:23], v[188:189] op_sel_hi:[1,0]
	v_pk_mul_f32 v[24:25], v[24:25], v[188:189] op_sel_hi:[1,0]
	v_pk_mul_f32 v[26:27], v[26:27], v[188:189] op_sel_hi:[1,0]
	v_pk_mul_f32 v[28:29], v[28:29], v[188:189] op_sel_hi:[1,0]
	v_pk_mul_f32 v[30:31], v[30:31], v[188:189] op_sel_hi:[1,0]
	v_pk_mul_f32 v[32:33], v[32:33], v[188:189] op_sel_hi:[1,0]
.Lda_dl_nr6:
	v_fma_f32 v66, v66, s75, -v224
	v_exp_f32_e32 v66, v66
	v_fma_f32 v67, v67, s75, -v224
	v_exp_f32_e32 v67, v67
	v_fma_f32 v68, v68, s75, -v224
	v_exp_f32_e32 v68, v68
	v_fma_f32 v69, v69, s75, -v224
	v_exp_f32_e32 v69, v69
	v_add_f32_e32 v193, v68, v66
	v_fma_f32 v70, v70, s75, -v224
	s_waitcnt lgkmcnt(4)
	v_mfma_f32_32x32x16_bf16 v[226:241], v[242:245], v[90:93], 0
	v_exp_f32_e32 v70, v70
	v_add_f32_e32 v194, v69, v67
	v_fma_f32 v71, v71, s75, -v224
	v_exp_f32_e32 v71, v71
	v_add_f32_e32 v193, v70, v193
	v_fma_f32 v72, v72, s75, -v224
	v_exp_f32_e32 v72, v72
	v_add_f32_e32 v194, v71, v194
	v_fma_f32 v73, v73, s75, -v224
	v_exp_f32_e32 v73, v73
	v_add_f32_e32 v193, v72, v193
	v_fma_f32 v74, v74, s75, -v224
	v_exp_f32_e32 v74, v74
	v_add_f32_e32 v194, v73, v194
	v_fma_f32 v75, v75, s75, -v224
	v_exp_f32_e32 v75, v75
	v_add_f32_e32 v193, v74, v193
	v_fma_f32 v76, v76, s75, -v224
	v_mfma_f32_32x32x16_bf16 v[226:241], v[246:249], v[94:97], v[226:241]
	v_exp_f32_e32 v76, v76
	v_add_f32_e32 v194, v75, v194
	v_fma_f32 v77, v77, s75, -v224
	v_exp_f32_e32 v77, v77
	v_add_f32_e32 v193, v76, v193
	v_fma_f32 v78, v78, s75, -v224
	v_exp_f32_e32 v78, v78
	v_add_f32_e32 v194, v77, v194
	v_fma_f32 v79, v79, s75, -v224
	v_exp_f32_e32 v79, v79
	v_add_f32_e32 v193, v78, v193
	v_fma_f32 v80, v80, s75, -v224
	v_exp_f32_e32 v80, v80
	v_add_f32_e32 v194, v79, v194
	v_fma_f32 v81, v81, s75, -v224
	v_exp_f32_e32 v81, v81
	v_add_f32_e32 v193, v80, v193
	v_add_f32_e32 v194, v81, v194
	v_add_f32_e32 v193, v193, v194
	v_cvt_pk_bf16_f32 v242, v66, v67
	v_cvt_pk_bf16_f32 v243, v68, v69
	v_cvt_pk_bf16_f32 v244, v70, v71
	v_cvt_pk_bf16_f32 v245, v72, v73
	v_cvt_pk_bf16_f32 v246, v74, v75
	v_cvt_pk_bf16_f32 v247, v76, v77
	v_cvt_pk_bf16_f32 v248, v78, v79
	v_cvt_pk_bf16_f32 v249, v80, v81
	v_add_f32_e32 v157, v157, v193
	s_waitcnt lgkmcnt(0)
	s_nop 1
	v_mfma_f32_32x32x16_bf16 v[50:65], v[142:145], v[242:245], v[50:65]
	v_max3_f32 v185, v226, v227, v228
	v_mfma_f32_32x32x16_bf16 v[18:33], v[134:137], v[242:245], v[18:33]
	v_max3_f32 v185, v185, v229, v230
	v_max3_f32 v185, v185, v231, v232
	v_mfma_f32_32x32x16_bf16 v[50:65], v[138:141], v[246:249], v[50:65]
	v_max3_f32 v185, v185, v233, v234
	v_max3_f32 v185, v185, v235, v236
	v_mfma_f32_32x32x16_bf16 v[18:33], v[130:133], v[246:249], v[18:33]
	v_max3_f32 v185, v185, v237, v238
	v_max3_f32 v185, v185, v239, v240
	v_max_f32_e32 v185, v185, v241
	v_fma_f32 v188, v185, s75, -v223
	v_cmp_lt_f32_e32 vcc, s73, v188
	s_cbranch_vccz .Lda_dl_nr7
	v_mov_b32_e32 v188, v185
	s_nop 1
	v_permlane32_swap_b32_e32 v185, v188
	v_max_f32_e32 v185, v185, v188
	v_mul_f32_e32 v185, 0x3e8293ee, v185
	v_max_f32_e32 v185, v223, v185
	v_sub_f32_e32 v188, v223, v185
	v_exp_f32_e32 v188, v188
	v_mov_b32_e32 v223, v185
	s_nop 0
	v_mul_f32_e32 v155, v155, v188
	v_pk_mul_f32 v[34:35], v[34:35], v[188:189] op_sel_hi:[1,0]
	v_pk_mul_f32 v[36:37], v[36:37], v[188:189] op_sel_hi:[1,0]
	v_pk_mul_f32 v[38:39], v[38:39], v[188:189] op_sel_hi:[1,0]
	v_pk_mul_f32 v[40:41], v[40:41], v[188:189] op_sel_hi:[1,0]
	v_pk_mul_f32 v[42:43], v[42:43], v[188:189] op_sel_hi:[1,0]
	v_pk_mul_f32 v[44:45], v[44:45], v[188:189] op_sel_hi:[1,0]
	v_pk_mul_f32 v[46:47], v[46:47], v[188:189] op_sel_hi:[1,0]
	v_pk_mul_f32 v[48:49], v[48:49], v[188:189] op_sel_hi:[1,0]
	v_pk_mul_f32 v[2:3], v[2:3], v[188:189] op_sel_hi:[1,0]
	v_pk_mul_f32 v[4:5], v[4:5], v[188:189] op_sel_hi:[1,0]
	v_pk_mul_f32 v[6:7], v[6:7], v[188:189] op_sel_hi:[1,0]
	v_pk_mul_f32 v[8:9], v[8:9], v[188:189] op_sel_hi:[1,0]
	v_pk_mul_f32 v[10:11], v[10:11], v[188:189] op_sel_hi:[1,0]
	v_pk_mul_f32 v[12:13], v[12:13], v[188:189] op_sel_hi:[1,0]
	v_pk_mul_f32 v[14:15], v[14:15], v[188:189] op_sel_hi:[1,0]
	v_pk_mul_f32 v[16:17], v[16:17], v[188:189] op_sel_hi:[1,0]
.Lda_dl_nr7:
	v_fma_f32 v226, v226, s75, -v223
	v_exp_f32_e32 v226, v226
	v_fma_f32 v227, v227, s75, -v223
	v_exp_f32_e32 v227, v227
	v_fma_f32 v228, v228, s75, -v223
	v_exp_f32_e32 v228, v228
	v_fma_f32 v229, v229, s75, -v223
	v_exp_f32_e32 v229, v229
	v_add_f32_e32 v193, v228, v226
	v_fma_f32 v230, v230, s75, -v223
	v_exp_f32_e32 v230, v230
	v_add_f32_e32 v194, v229, v227
	v_fma_f32 v231, v231, s75, -v223
	v_exp_f32_e32 v231, v231
	v_add_f32_e32 v193, v230, v193
	v_fma_f32 v232, v232, s75, -v223
	v_exp_f32_e32 v232, v232
	v_add_f32_e32 v194, v231, v194
	v_fma_f32 v233, v233, s75, -v223
	v_exp_f32_e32 v233, v233
	v_add_f32_e32 v193, v232, v193
	v_fma_f32 v234, v234, s75, -v223
	v_exp_f32_e32 v234, v234
	v_add_f32_e32 v194, v233, v194
	v_fma_f32 v235, v235, s75, -v223
	v_exp_f32_e32 v235, v235
	v_add_f32_e32 v193, v234, v193
	v_fma_f32 v236, v236, s75, -v223
	v_exp_f32_e32 v236, v236
	v_add_f32_e32 v194, v235, v194
	v_fma_f32 v237, v237, s75, -v223
	v_exp_f32_e32 v237, v237
	v_add_f32_e32 v193, v236, v193
	v_fma_f32 v238, v238, s75, -v223
	v_exp_f32_e32 v238, v238
	v_add_f32_e32 v194, v237, v194
	v_fma_f32 v239, v239, s75, -v223
	v_exp_f32_e32 v239, v239
	v_add_f32_e32 v193, v238, v193
	v_fma_f32 v240, v240, s75, -v223
	v_exp_f32_e32 v240, v240
	v_add_f32_e32 v194, v239, v194
	v_fma_f32 v241, v241, s75, -v223
	v_exp_f32_e32 v241, v241
	v_add_f32_e32 v193, v240, v193
	v_add_f32_e32 v194, v241, v194
	v_add_f32_e32 v193, v193, v194
	v_cvt_pk_bf16_f32 v242, v226, v227
	v_cvt_pk_bf16_f32 v243, v228, v229
	v_cvt_pk_bf16_f32 v244, v230, v231
	v_cvt_pk_bf16_f32 v245, v232, v233
	v_cvt_pk_bf16_f32 v246, v234, v235
	v_cvt_pk_bf16_f32 v247, v236, v237
	v_cvt_pk_bf16_f32 v248, v238, v239
	v_cvt_pk_bf16_f32 v249, v240, v241
	v_add_f32_e32 v155, v155, v193
	s_nop 1
	v_mfma_f32_32x32x16_bf16 v[34:49], v[142:145], v[242:245], v[34:49]
	v_mfma_f32_32x32x16_bf16 v[2:17], v[134:137], v[242:245], v[2:17]
	v_mfma_f32_32x32x16_bf16 v[34:49], v[138:141], v[246:249], v[34:49]
	v_mfma_f32_32x32x16_bf16 v[2:17], v[130:133], v[246:249], v[2:17]
